# static s_setprio 1 for waves 4-7 during the sgu items (strategy 4 on the sgu MFMA groups)
# baseline (speedup 1.0000x reference)
; DI u16 f2bf(float a) { return (u16)(pack2(a, 0.f) & 0xffffu); }
; DI float bflo(unsigned v) { return __uint_as_float(v << 16); }
; DI float bfhi(unsigned v) { return __uint_as_float(v & 0xffff0000u); }
; DI int tid_() { int t = threadIdx.x; asm volatile("" : "+v"(t)); return t; }
;   const int tid = tid_(), wid = tid >> 6, lane = tid & 63, fr = lane & 15, fq = lane >> 4;
;   u16* vT = (u16*)shm;
;   float* st = (float*)(shm + 128 * 136 * 2);
;   const u16* projA = (const u16*)(P.ws + OFF_PROJA);
;   u16* actA = (u16*)(P.ws + OFF_ACTA);
;   const u16* Wsgu = (const u16*)(P.ws + OFF_W) + W_SGU;
;   const float* lng = P.ln_v_g + l * 512;
;   const float* lnb = P.ln_v_b + l * 512;
;   const float* sb = P.sgu_b + l * 512;
;   for (int nb = blockIdx.x; nb < 256; nb += gridDim.x) {
;     const int T0 = nb * 128;
;     {
;       const int tok = tid >> 2, qu = tid & 3;
;       const u16* p = projA + (size_t)(T0 + tok) * 1024 + 512 + qu * 128;
;     ...
;     for (int g = 0; g < 4; ++g) {
;       {
;         const int s = tid >> 2, cq = tid & 3;
;         const float mean = st[s], rstd = st[128 + s];
;         const u16* p = projA + (size_t)(T0 + s) * 1024 + 512 + g * 128 + cq * 32;
; #pragma unroll
;         for (int i = 0; i < 4; ++i) {
;           i32x4 v = *(const i32x4*)(p + i * 8);
; #pragma unroll
;           for (int e = 0; e < 4; ++e) {
;             const int c = cq * 32 + i * 8 + 2 * e;
;             float a = (bflo((unsigned)v[e]) - mean) * rstd * lng[g * 128 + c] + lnb[g * 128 + c];
;             float d = (bfhi((unsigned)v[e]) - mean) * rstd * lng[g * 128 + c + 1] + lnb[g * 128 + c + 1];
;             vT[c * 136 + s] = f2bf(a);
;             vT[(c + 1) * 136 + s] = f2bf(d);
;           }
;         }
;       }
;       __syncthreads();
;       f32x4 acc[8];
; #pragma unroll
;       for (int i = 0; i < 8; ++i) acc[i] = f32x4{0.f, 0.f, 0.f, 0.f};
;       const u16* wp = Wsgu + (size_t)(g * 128 + wid * 16 + fr) * 128 + fq * 8;
; #pragma unroll
;       for (int ks = 0; ks < 4; ++ks) {
;         bf16x8 af = *(const bf16x8*)(wp + ks * 32);
; #pragma unroll
;         for (int ns = 0; ns < 8; ++ns) {
;           bf16x8 bfr = *(const bf16x8*)(vT + (ns * 16 + fr) * 136 + ks * 32 + fq * 8);
.LBB0_776:
	s_or_b64 exec, exec, s[0:1]
	v_readlane_b32 s12, v253, 2
	v_readlane_b32 s13, v253, 3
	s_mov_b64 s[10:11], s[54:55]
	v_readlane_b32 s16, v253, 6
	v_readlane_b32 s17, v253, 7
	v_readlane_b32 s18, v253, 8
	v_readlane_b32 s19, v253, 9
	v_readlane_b32 s20, v253, 10
	v_readlane_b32 s21, v253, 11
	v_readlane_b32 s22, v253, 12
	v_readlane_b32 s23, v253, 13
	v_readlane_b32 s24, v253, 14
	v_readlane_b32 s25, v253, 15
	v_readlane_b32 s26, v253, 16
	v_readlane_b32 s27, v253, 17
	s_mov_b64 s[8:9], s[12:13]
	s_mov_b64 s[0:1], s[12:13]
	s_mov_b64 s[4:5], s[66:67]
	v_mov_b32_e32 v0, v135
	s_and_b64 vcc, exec, s[6:7]
	s_barrier
	v_readlane_b32 s14, v253, 4
	v_readlane_b32 s15, v253, 5
	s_cbranch_vccnz .LBB0_784
	v_ashrrev_i32_e32 v29, 2, v0
	v_and_b32_e32 v3, 3, v0
	v_and_b32_e32 v64, -4, v0
	v_lshlrev_b32_e32 v8, 1, v29
	v_mul_u32_u24_e32 v11, 0x1100, v3
	v_sub_u32_e32 v9, v64, v8
	v_lshlrev_b32_e32 v11, 1, v11
	v_add_u32_e32 v66, v9, v11
	v_add_u32_e32 v67, v11, v8
	v_lshl_or_b32 v11, v3, 5, 2
	v_mul_u32_u24_e32 v11, 0x88, v11
	v_lshlrev_b32_e32 v11, 1, v11
	v_add_u32_e32 v14, 0x220, v11
	v_add_u32_e32 v70, v9, v14
	v_add_u32_e32 v71, v14, v8
	v_add_u32_e32 v14, 0x440, v11
	v_add_u32_e32 v72, v9, v14
	v_add_u32_e32 v73, v14, v8
	v_add_u32_e32 v14, 0x660, v11
	v_add_u32_e32 v74, v9, v14
	v_add_u32_e32 v75, v14, v8
	v_add_u32_e32 v14, 0x880, v11
	v_add_u32_e32 v76, v9, v14
	v_add_u32_e32 v77, v14, v8
	v_add_u32_e32 v14, 0xaa0, v11
	v_add_u32_e32 v78, v9, v14
	v_add_u32_e32 v79, v14, v8
	v_add_u32_e32 v14, 0xcc0, v11
	v_add_u32_e32 v80, v9, v14
	v_add_u32_e32 v81, v14, v8
	v_add_u32_e32 v14, 0xee0, v11
	s_mov_b64 s[12:13], s[16:17]
	v_add_u32_e32 v82, v9, v14
	v_add_u32_e32 v83, v14, v8
	v_add_u32_e32 v14, 0x1100, v11
	s_add_u32 s12, s10, 0x19000000
	v_add_u32_e32 v84, v9, v14
	v_add_u32_e32 v85, v14, v8
	v_add_u32_e32 v14, 0x1320, v11
	s_mov_b64 s[14:15], s[18:19]
	s_addc_u32 s13, s11, 0
	s_lshl_b64 s[0:1], s[78:79], 2
	v_readlane_b32 s36, v253, 18
	v_add_u32_e32 v86, v9, v14
	v_add_u32_e32 v87, v14, v8
	v_add_u32_e32 v14, 0x1540, v11
	v_readlane_b32 s37, v253, 19
	s_add_u32 s14, s36, s0
	v_and_b32_e32 v4, 48, v0
	v_mov_b32_e32 v5, v133
	v_add_u32_e32 v88, v9, v14
	v_add_u32_e32 v89, v14, v8
	v_add_u32_e32 v14, 0x1760, v11
	s_addc_u32 s15, s37, s1
	v_lshl_add_u64 v[6:7], s[10:11], 0, v[4:5]
	s_mov_b64 s[0:1], 0x1ca0000
	v_add_u32_e32 v90, v9, v14
	v_add_u32_e32 v91, v14, v8
	v_add_u32_e32 v14, 0x1980, v11
	v_lshl_add_u64 v[12:13], v[6:7], 0, s[0:1]
	v_add_u32_e32 v68, v9, v11
	v_add_u32_e32 v69, v11, v8
	v_add_u32_e32 v92, v9, v14
	v_add_u32_e32 v93, v14, v8
	v_add_u32_e32 v14, 0x1ba0, v11
	v_add_u32_e32 v11, 0x1dc0, v11
	v_readlane_b32 s0, v252, 14
	v_and_b32_e32 v1, 15, v0
	v_bfi_b32 v65, -16, v29, v0
	v_lshlrev_b32_e32 v6, 5, v0
	v_ashrrev_i32_e32 v7, 4, v0
	v_add_u32_e32 v94, v9, v14
	v_add_u32_e32 v95, v14, v8
	v_add_u32_e32 v96, v9, v11
	v_add_u32_e32 v9, 0x200, v0
	v_add_u32_e32 v14, 0x400, v0
	v_add_u32_e32 v0, 0x600, v0
	v_readlane_b32 s1, v252, 15
	v_lshlrev_b32_e32 v2, 7, v3
	v_ashrrev_i32_e32 v9, 4, v9
	v_ashrrev_i32_e32 v17, 4, v14
	v_ashrrev_i32_e32 v0, 4, v0
	v_readlane_b32 s4, v252, 5
	s_lshl_b64 s[0:1], s[0:1], 11
	s_mov_b64 s[16:17], s[20:21]
	s_mov_b64 s[18:19], s[22:23]
	s_mov_b64 s[20:21], s[24:25]
	v_readlane_b32 s47, v253, 29
	v_mul_lo_u32 v5, v65, s68
	v_and_b32_e32 v6, 0x1e0, v6
	v_mul_lo_u32 v10, v7, s68
	v_add_u32_e32 v97, v11, v8
	v_mul_u32_u24_e32 v8, 0x110, v1
	v_mul_lo_u32 v11, v9, s68
	v_mul_lo_u32 v19, v17, s68
	v_mul_lo_u32 v21, v0, s68
	v_lshlrev_b32_e32 v23, 4, v1
	v_add_u32_e32 v22, s4, v0
	v_or_b32_e32 v0, s0, v2
	v_mov_b32_e32 v1, s1
	s_mov_b32 s47, s90
	v_cmp_eq_u32_e64 s[8:9], 0, v3
	v_or_b32_e32 v14, 0x19000000, v23
	v_mov_b32_e32 v15, v133
	v_add_u32_e32 v16, s4, v7
	v_add_u32_e32 v18, s4, v9
	v_add_u32_e32 v20, s4, v17
	v_lshl_add_u64 v[24:25], s[18:19], 0, v[0:1]
	v_lshl_add_u64 v[26:27], s[20:21], 0, v[0:1]
	v_lshlrev_b32_e32 v28, 6, v3
	v_add_u32_e32 v30, s4, v29
	v_or_b32_e32 v32, 0x7000000, v23
	v_mov_b32_e32 v33, v133
	v_lshlrev_b32_e32 v132, 1, v2
	v_add_u32_e32 v98, v4, v8
	v_add_u32_e32 v99, v5, v4
	v_add_u32_e32 v100, v6, v10
	v_add_u32_e32 v101, v6, v11
	v_add_u32_e32 v102, v6, v19
	v_add_u32_e32 v103, v6, v21
	s_mov_b32 s4, s90
	s_mov_b64 s[22:23], s[26:27]
	v_readlane_b32 s38, v253, 20
	v_readlane_b32 s39, v253, 21
	v_readlane_b32 s40, v253, 22
	v_readlane_b32 s41, v253, 23
	v_readlane_b32 s42, v253, 24
	v_readlane_b32 s43, v253, 25
	v_readlane_b32 s44, v253, 26
	v_readlane_b32 s45, v253, 27
	v_readlane_b32 s46, v253, 28
	v_readlane_b32 s48, v253, 30
	v_readlane_b32 s49, v253, 31
	v_readlane_b32 s50, v253, 32
	v_readlane_b32 s51, v253, 33
.LBB0_778:
	v_readfirstlane_b32 s98, v135
	s_nop 0
	s_cmp_lt_u32 s98, 0x100
	s_cbranch_scc1 .Lsp_skips
	s_setprio 1
; DI float bflo(unsigned v) { return __uint_as_float(v << 16); }
; DI float bfhi(unsigned v) { return __uint_as_float(v & 0xffff0000u); }
;     ...
;       const int tok = tid >> 2, qu = tid & 3;
;       const u16* p = projA + (size_t)(T0 + tok) * 1024 + 512 + qu * 128;
;       float s1 = 0.f, s2 = 0.f;
; #pragma unroll
;       for (int i = 0; i < 16; ++i) {
;         i32x4 v = *(const i32x4*)(p + i * 8);
; #pragma unroll
;         for (int e = 0; e < 4; ++e) {
;           float a = bflo((unsigned)v[e]), c = bfhi((unsigned)v[e]);
;           s1 += a + c;
;           s2 += a * a + c * c;
;         }
;       }
.Lsp_skips:
	v_lshl_add_u32 v0, s4, 7, v29
	v_ashrrev_i32_e32 v1, 31, v0
	v_lshlrev_b64 v[0:1], 11, v[0:1]
	v_lshl_add_u64 v[0:1], s[12:13], 0, v[0:1]
	v_lshl_add_u64 v[0:1], v[0:1], 0, v[132:133]
	global_load_dwordx4 v[136:139], v[0:1], off offset:1024
	global_load_dwordx4 v[140:143], v[0:1], off offset:1040
	global_load_dwordx4 v[144:147], v[0:1], off offset:1056
	global_load_dwordx4 v[148:151], v[0:1], off offset:1072
	global_load_dwordx4 v[152:155], v[0:1], off offset:1088
	global_load_dwordx4 v[156:159], v[0:1], off offset:1104
	global_load_dwordx4 v[160:163], v[0:1], off offset:1120
	global_load_dwordx4 v[164:167], v[0:1], off offset:1136
	global_load_dwordx4 v[168:171], v[0:1], off offset:1152
	global_load_dwordx4 v[172:175], v[0:1], off offset:1168
	global_load_dwordx4 v[176:179], v[0:1], off offset:1184
	global_load_dwordx4 v[180:183], v[0:1], off offset:1216
	global_load_dwordx4 v[184:187], v[0:1], off offset:1200
	global_load_dwordx4 v[188:191], v[0:1], off offset:1232
	global_load_dwordx4 v[192:195], v[0:1], off offset:1248
	global_load_dwordx4 v[196:199], v[0:1], off offset:1264
	s_waitcnt vmcnt(15) lgkmcnt(0)
	v_lshlrev_b32_e32 v11, 16, v137
	v_and_b32_e32 v7, 0xffff0000, v136
	v_lshlrev_b32_e32 v10, 16, v136
	v_mov_b32_e32 v2, v11
	v_and_b32_e32 v9, 0xffff0000, v137
	v_mov_b32_e32 v3, v137
	v_pk_mul_f32 v[36:37], v[10:11], v[2:3] op_sel:[1,0] op_sel_hi:[0,1]
	v_pk_add_f32 v[2:3], v[10:11], v[6:7] op_sel:[1,0] op_sel_hi:[0,1]
	v_mov_b32_e32 v37, v3
	v_lshlrev_b32_e32 v39, 16, v138
	v_and_b32_e32 v41, 0xffff0000, v138
	v_lshlrev_b32_e32 v43, 16, v139
	v_and_b32_e32 v45, 0xffff0000, v139
	v_mul_f32_e32 v34, v10, v10
	v_mul_f32_e32 v6, v9, v9
	v_mov_b32_e32 v35, v11
	v_mul_f32_e32 v8, v7, v7
	v_mov_b32_e32 v7, v133
	v_mul_f32_e32 v38, v39, v39
	v_mul_f32_e32 v40, v41, v41
	v_pk_add_f32 v[8:9], v[34:35], v[8:9]
	v_pk_add_f32 v[6:7], v[36:37], v[6:7]
	v_mul_f32_e32 v42, v43, v43
	v_mul_f32_e32 v44, v45, v45
	v_pk_add_f32 v[6:7], v[8:9], v[6:7]
	v_pk_add_f32 v[8:9], v[38:39], v[40:41]
	s_waitcnt vmcnt(14) lgkmcnt(0)
	v_lshlrev_b32_e32 v47, 16, v140
	v_and_b32_e32 v49, 0xffff0000, v140
	v_lshlrev_b32_e32 v51, 16, v141
	v_and_b32_e32 v53, 0xffff0000, v141
	v_lshlrev_b32_e32 v55, 16, v142
	v_and_b32_e32 v57, 0xffff0000, v142
	v_lshlrev_b32_e32 v59, 16, v143
	v_and_b32_e32 v61, 0xffff0000, v143
	v_mul_f32_e32 v46, v47, v47
	v_mul_f32_e32 v48, v49, v49
	v_pk_add_f32 v[6:7], v[8:9], v[6:7]
	v_pk_add_f32 v[8:9], v[42:43], v[44:45]
	v_mul_f32_e32 v50, v51, v51
	v_mul_f32_e32 v52, v53, v53
	v_pk_add_f32 v[6:7], v[8:9], v[6:7]
	v_pk_add_f32 v[8:9], v[46:47], v[48:49]
	v_mul_f32_e32 v54, v55, v55
	v_mul_f32_e32 v56, v57, v57
	v_pk_add_f32 v[6:7], v[8:9], v[6:7]
	v_pk_add_f32 v[8:9], v[50:51], v[52:53]
	v_mul_f32_e32 v58, v59, v59
	v_mul_f32_e32 v60, v61, v61
	v_pk_add_f32 v[6:7], v[8:9], v[6:7]
	v_pk_add_f32 v[8:9], v[54:55], v[56:57]
	s_waitcnt vmcnt(13) lgkmcnt(0)
	v_lshlrev_b32_e32 v63, 16, v144
	v_and_b32_e32 v105, 0xffff0000, v144
	v_mul_f32_e32 v62, v63, v63
	v_mul_f32_e32 v104, v105, v105
	v_lshlrev_b32_e32 v107, 16, v145
	v_and_b32_e32 v3, 0xffff0000, v145
	v_pk_add_f32 v[6:7], v[8:9], v[6:7]
	v_pk_add_f32 v[8:9], v[58:59], v[60:61]
	v_mul_f32_e32 v106, v107, v107
	v_mul_f32_e32 v2, v3, v3
	v_lshlrev_b32_e32 v109, 16, v146
	v_and_b32_e32 v111, 0xffff0000, v146
	v_pk_add_f32 v[6:7], v[8:9], v[6:7]
	v_pk_add_f32 v[8:9], v[62:63], v[104:105]
	v_mul_f32_e32 v108, v109, v109
	v_mul_f32_e32 v110, v111, v111
	v_pk_add_f32 v[6:7], v[8:9], v[6:7]
	v_pk_add_f32 v[2:3], v[106:107], v[2:3]
	s_nop 0
	v_pk_add_f32 v[2:3], v[2:3], v[6:7]
	v_pk_add_f32 v[6:7], v[108:109], v[110:111]
	s_nop 0
	v_pk_add_f32 v[2:3], v[6:7], v[2:3]
	v_lshlrev_b32_e32 v7, 16, v147
	v_and_b32_e32 v5, 0xffff0000, v147
	v_mul_f32_e32 v6, v7, v7
	v_mul_f32_e32 v4, v5, v5
	v_pk_add_f32 v[4:5], v[6:7], v[4:5]
	v_pk_add_f32 v[2:3], v[4:5], v[2:3]
	s_waitcnt vmcnt(12) lgkmcnt(0)
	v_lshlrev_b32_e32 v11, 16, v148
	v_and_b32_e32 v35, 0xffff0000, v148
	v_lshlrev_b32_e32 v37, 16, v149
	v_and_b32_e32 v39, 0xffff0000, v149
	v_lshlrev_b32_e32 v41, 16, v150
	v_and_b32_e32 v43, 0xffff0000, v150
	v_lshlrev_b32_e32 v45, 16, v151
	v_and_b32_e32 v47, 0xffff0000, v151
	v_mul_f32_e32 v10, v11, v11
	v_mul_f32_e32 v34, v35, v35
	v_mul_f32_e32 v36, v37, v37
	v_mul_f32_e32 v38, v39, v39
	v_pk_add_f32 v[4:5], v[10:11], v[34:35]
	v_mul_f32_e32 v40, v41, v41
	v_mul_f32_e32 v42, v43, v43
	v_pk_add_f32 v[2:3], v[4:5], v[2:3]
	v_pk_add_f32 v[4:5], v[36:37], v[38:39]
	v_mul_f32_e32 v44, v45, v45
	v_mul_f32_e32 v46, v47, v47
	v_pk_add_f32 v[2:3], v[4:5], v[2:3]
	v_pk_add_f32 v[4:5], v[40:41], v[42:43]
	s_waitcnt vmcnt(11) lgkmcnt(0)
	v_lshlrev_b32_e32 v49, 16, v152
	v_and_b32_e32 v51, 0xffff0000, v152
	v_lshlrev_b32_e32 v53, 16, v153
	v_and_b32_e32 v55, 0xffff0000, v153
	v_lshlrev_b32_e32 v57, 16, v154
	v_and_b32_e32 v59, 0xffff0000, v154
	v_lshlrev_b32_e32 v61, 16, v155
	v_and_b32_e32 v63, 0xffff0000, v155
	v_pk_add_f32 v[2:3], v[4:5], v[2:3]
	v_pk_add_f32 v[4:5], v[44:45], v[46:47]
	v_mul_f32_e32 v48, v49, v49
	v_mul_f32_e32 v50, v51, v51
	v_mul_f32_e32 v52, v53, v53
	v_mul_f32_e32 v54, v55, v55
	v_pk_add_f32 v[2:3], v[4:5], v[2:3]
	v_pk_add_f32 v[4:5], v[48:49], v[50:51]
	v_mul_f32_e32 v56, v57, v57
	v_mul_f32_e32 v58, v59, v59
	v_pk_add_f32 v[2:3], v[4:5], v[2:3]
	v_pk_add_f32 v[4:5], v[52:53], v[54:55]
	v_mul_f32_e32 v60, v61, v61
	v_mul_f32_e32 v62, v63, v63
	v_pk_add_f32 v[2:3], v[4:5], v[2:3]
	v_pk_add_f32 v[4:5], v[56:57], v[58:59]
	s_waitcnt vmcnt(9) lgkmcnt(0)
; DI float bflo(unsigned v) { return __uint_as_float(v << 16); }
; DI float bfhi(unsigned v) { return __uint_as_float(v & 0xffff0000u); }
;     ...
;       for (int i = 0; i < 16; ++i) {
;         i32x4 v = *(const i32x4*)(p + i * 8);
; #pragma unroll
;         for (int e = 0; e < 4; ++e) {
;           float a = bflo((unsigned)v[e]), c = bfhi((unsigned)v[e]);
;           s1 += a + c;
;           s2 += a * a + c * c;
;         }
;       }
	v_lshlrev_b32_e32 v105, 16, v156
	v_and_b32_e32 v107, 0xffff0000, v156
	v_mul_f32_e32 v104, v105, v105
	v_mul_f32_e32 v106, v107, v107
	v_lshlrev_b32_e32 v109, 16, v157
	v_and_b32_e32 v7, 0xffff0000, v157
	v_pk_add_f32 v[2:3], v[4:5], v[2:3]
	v_pk_add_f32 v[4:5], v[60:61], v[62:63]
	v_mul_f32_e32 v108, v109, v109
	v_mul_f32_e32 v6, v7, v7
	v_pk_add_f32 v[2:3], v[4:5], v[2:3]
	v_pk_add_f32 v[4:5], v[104:105], v[106:107]
	v_lshlrev_b32_e32 v11, 16, v160
	v_pk_add_f32 v[2:3], v[4:5], v[2:3]
	v_pk_add_f32 v[4:5], v[108:109], v[6:7]
	v_and_b32_e32 v7, 0xffff0000, v158
	v_pk_add_f32 v[2:3], v[4:5], v[2:3]
	v_lshlrev_b32_e32 v5, 16, v158
	v_mul_f32_e32 v4, v5, v5
	v_mul_f32_e32 v6, v7, v7
	v_pk_add_f32 v[4:5], v[4:5], v[6:7]
	v_lshlrev_b32_e32 v7, 16, v159
	v_and_b32_e32 v9, 0xffff0000, v159
	v_mul_f32_e32 v6, v7, v7
	v_mul_f32_e32 v8, v9, v9
	v_and_b32_e32 v35, 0xffff0000, v160
	v_mul_f32_e32 v10, v11, v11
	v_mul_f32_e32 v34, v35, v35
	v_lshlrev_b32_e32 v37, 16, v161
	v_and_b32_e32 v39, 0xffff0000, v161
	v_pk_add_f32 v[2:3], v[4:5], v[2:3]
	v_pk_add_f32 v[4:5], v[6:7], v[8:9]
	v_mul_f32_e32 v36, v37, v37
	v_mul_f32_e32 v38, v39, v39
	v_pk_add_f32 v[2:3], v[4:5], v[2:3]
	v_pk_add_f32 v[4:5], v[10:11], v[34:35]
	v_pk_add_f32 v[2:3], v[4:5], v[2:3]
	v_pk_add_f32 v[4:5], v[36:37], v[38:39]
	v_lshlrev_b32_e32 v41, 16, v162
	v_and_b32_e32 v43, 0xffff0000, v162
	v_mul_f32_e32 v40, v41, v41
	v_mul_f32_e32 v42, v43, v43
	v_lshlrev_b32_e32 v45, 16, v163
	v_and_b32_e32 v47, 0xffff0000, v163
	v_mul_f32_e32 v44, v45, v45
	v_mul_f32_e32 v46, v47, v47
	v_pk_add_f32 v[2:3], v[4:5], v[2:3]
	v_pk_add_f32 v[4:5], v[40:41], v[42:43]
	s_waitcnt vmcnt(6) lgkmcnt(0)
	v_lshlrev_b32_e32 v49, 16, v164
	v_and_b32_e32 v51, 0xffff0000, v164
	v_mul_f32_e32 v48, v49, v49
	v_mul_f32_e32 v50, v51, v51
	v_lshlrev_b32_e32 v53, 16, v165
	v_and_b32_e32 v55, 0xffff0000, v165
	v_pk_add_f32 v[2:3], v[4:5], v[2:3]
	v_pk_add_f32 v[4:5], v[44:45], v[46:47]
	v_mul_f32_e32 v52, v53, v53
	v_mul_f32_e32 v54, v55, v55
	v_pk_add_f32 v[2:3], v[4:5], v[2:3]
	v_pk_add_f32 v[4:5], v[48:49], v[50:51]
	v_lshlrev_b32_e32 v57, 16, v166
	v_pk_add_f32 v[2:3], v[4:5], v[2:3]
	v_pk_add_f32 v[4:5], v[52:53], v[54:55]
	v_lshlrev_b32_e32 v41, 16, v172
	v_and_b32_e32 v43, 0xffff0000, v172
	v_lshlrev_b32_e32 v45, 16, v173
	v_and_b32_e32 v47, 0xffff0000, v173
	v_lshlrev_b32_e32 v49, 16, v174
	v_and_b32_e32 v51, 0xffff0000, v174
	v_lshlrev_b32_e32 v53, 16, v175
	v_and_b32_e32 v55, 0xffff0000, v175
	v_and_b32_e32 v59, 0xffff0000, v166
	v_mul_f32_e32 v56, v57, v57
	v_mul_f32_e32 v58, v59, v59
	v_lshlrev_b32_e32 v61, 16, v167
	v_and_b32_e32 v63, 0xffff0000, v167
	v_mul_f32_e32 v60, v61, v61
	v_mul_f32_e32 v62, v63, v63
	v_lshlrev_b32_e32 v109, 16, v168
	v_and_b32_e32 v111, 0xffff0000, v168
	v_pk_add_f32 v[2:3], v[4:5], v[2:3]
	v_pk_add_f32 v[4:5], v[56:57], v[58:59]
	v_mul_f32_e32 v108, v109, v109
	v_mul_f32_e32 v110, v111, v111
	v_pk_add_f32 v[2:3], v[4:5], v[2:3]
	v_pk_add_f32 v[4:5], v[60:61], v[62:63]
	v_and_b32_e32 v7, 0xffff0000, v169
	v_pk_add_f32 v[2:3], v[4:5], v[2:3]
	v_pk_add_f32 v[4:5], v[108:109], v[110:111]
	v_mul_f32_e32 v6, v7, v7
	v_pk_add_f32 v[2:3], v[4:5], v[2:3]
	v_lshlrev_b32_e32 v5, 16, v169
	v_mul_f32_e32 v4, v5, v5
	v_pk_add_f32 v[4:5], v[4:5], v[6:7]
	v_lshlrev_b32_e32 v7, 16, v170
	v_and_b32_e32 v9, 0xffff0000, v170
	v_mul_f32_e32 v6, v7, v7
	v_mul_f32_e32 v8, v9, v9
	v_lshlrev_b32_e32 v11, 16, v171
	v_and_b32_e32 v35, 0xffff0000, v171
	v_mul_f32_e32 v10, v11, v11
	v_mul_f32_e32 v34, v35, v35
	v_pk_add_f32 v[2:3], v[4:5], v[2:3]
	v_pk_add_f32 v[4:5], v[6:7], v[8:9]
	v_mul_f32_e32 v40, v41, v41
	v_mul_f32_e32 v42, v43, v43
	v_pk_add_f32 v[2:3], v[4:5], v[2:3]
	v_pk_add_f32 v[4:5], v[10:11], v[34:35]
	v_mul_f32_e32 v44, v45, v45
	v_pk_add_f32 v[2:3], v[4:5], v[2:3]
	v_pk_add_f32 v[4:5], v[40:41], v[42:43]
	v_mul_f32_e32 v46, v47, v47
	v_mul_f32_e32 v48, v49, v49
	v_mul_f32_e32 v50, v51, v51
	v_pk_add_f32 v[2:3], v[4:5], v[2:3]
	v_pk_add_f32 v[4:5], v[44:45], v[46:47]
	v_mul_f32_e32 v52, v53, v53
	v_mul_f32_e32 v54, v55, v55
	v_pk_add_f32 v[2:3], v[4:5], v[2:3]
	v_pk_add_f32 v[4:5], v[48:49], v[50:51]
	s_waitcnt vmcnt(4) lgkmcnt(0)
	v_lshlrev_b32_e32 v57, 16, v176
	v_and_b32_e32 v59, 0xffff0000, v176
	v_mul_f32_e32 v56, v57, v57
	v_mul_f32_e32 v58, v59, v59
	v_lshlrev_b32_e32 v61, 16, v177
	v_and_b32_e32 v37, 0xffff0000, v177
	v_pk_add_f32 v[2:3], v[4:5], v[2:3]
	v_pk_add_f32 v[4:5], v[52:53], v[54:55]
	v_mul_f32_e32 v60, v61, v61
	v_mul_f32_e32 v36, v37, v37
	v_lshlrev_b32_e32 v63, 16, v178
	v_and_b32_e32 v105, 0xffff0000, v178
	v_pk_add_f32 v[2:3], v[4:5], v[2:3]
	v_pk_add_f32 v[4:5], v[56:57], v[58:59]
	v_mul_f32_e32 v62, v63, v63
	v_mul_f32_e32 v104, v105, v105
	v_lshlrev_b32_e32 v107, 16, v179
	v_and_b32_e32 v39, 0xffff0000, v179
	v_pk_add_f32 v[2:3], v[4:5], v[2:3]
	v_pk_add_f32 v[4:5], v[60:61], v[36:37]
	v_mul_f32_e32 v106, v107, v107
	v_mul_f32_e32 v38, v39, v39
	v_pk_add_f32 v[2:3], v[4:5], v[2:3]
	v_pk_add_f32 v[4:5], v[62:63], v[104:105]
	v_lshlrev_b32_e32 v45, 16, v180
	v_pk_add_f32 v[2:3], v[4:5], v[2:3]
	v_pk_add_f32 v[4:5], v[106:107], v[38:39]
	v_and_b32_e32 v47, 0xffff0000, v180
	v_lshlrev_b32_e32 v49, 16, v181
	v_and_b32_e32 v51, 0xffff0000, v181
	v_lshlrev_b32_e32 v53, 16, v182
	v_and_b32_e32 v55, 0xffff0000, v182
	v_lshlrev_b32_e32 v57, 16, v183
	v_and_b32_e32 v59, 0xffff0000, v183
	v_pk_add_f32 v[2:3], v[4:5], v[2:3]
	v_mul_f32_e32 v44, v45, v45
	v_mul_f32_e32 v46, v47, v47
	v_mul_f32_e32 v48, v49, v49
	v_mul_f32_e32 v50, v51, v51
	v_mul_f32_e32 v52, v53, v53
	v_mul_f32_e32 v54, v55, v55
	v_mul_f32_e32 v56, v57, v57
	v_mul_f32_e32 v58, v59, v59
	s_waitcnt vmcnt(2) lgkmcnt(0)
; DI float bflo(unsigned v) { return __uint_as_float(v << 16); }
; DI float bfhi(unsigned v) { return __uint_as_float(v & 0xffff0000u); }
;     ...
;       for (int i = 0; i < 16; ++i) {
;         i32x4 v = *(const i32x4*)(p + i * 8);
; #pragma unroll
;         for (int e = 0; e < 4; ++e) {
;           float a = bflo((unsigned)v[e]), c = bfhi((unsigned)v[e]);
;           s1 += a + c;
;           s2 += a * a + c * c;
;         }
;       }
;       s1 += __shfl_xor(s1, 1); s2 += __shfl_xor(s2, 1);
;       s1 += __shfl_xor(s1, 2); s2 += __shfl_xor(s2, 2);
;       const float mean = s1 * (1.f / 512.f);
;       const float var = fmaxf(s2 * (1.f / 512.f) - mean * mean, 0.f);
;       if (qu == 0) { st[tok] = mean; st[128 + tok] = rsqrtf(var + EPS); }
	v_lshlrev_b32_e32 v5, 16, v184
	v_and_b32_e32 v7, 0xffff0000, v184
	v_mul_f32_e32 v4, v5, v5
	v_mul_f32_e32 v6, v7, v7
	v_pk_add_f32 v[4:5], v[4:5], v[6:7]
	v_lshlrev_b32_e32 v7, 16, v185
	v_and_b32_e32 v9, 0xffff0000, v185
	v_mul_f32_e32 v6, v7, v7
	v_mul_f32_e32 v8, v9, v9
	v_lshlrev_b32_e32 v11, 16, v186
	v_and_b32_e32 v35, 0xffff0000, v186
	v_mul_f32_e32 v10, v11, v11
	v_mul_f32_e32 v34, v35, v35
	v_lshlrev_b32_e32 v37, 16, v187
	v_and_b32_e32 v39, 0xffff0000, v187
	v_pk_add_f32 v[2:3], v[4:5], v[2:3]
	v_pk_add_f32 v[4:5], v[6:7], v[8:9]
	v_mul_f32_e32 v36, v37, v37
	v_mul_f32_e32 v38, v39, v39
	v_pk_add_f32 v[2:3], v[4:5], v[2:3]
	v_pk_add_f32 v[4:5], v[10:11], v[34:35]
	v_lshlrev_b32_e32 v61, 16, v188
	v_pk_add_f32 v[2:3], v[4:5], v[2:3]
	v_pk_add_f32 v[4:5], v[36:37], v[38:39]
	v_and_b32_e32 v63, 0xffff0000, v188
	v_pk_add_f32 v[2:3], v[4:5], v[2:3]
	v_pk_add_f32 v[4:5], v[44:45], v[46:47]
	v_mul_f32_e32 v60, v61, v61
	v_pk_add_f32 v[2:3], v[4:5], v[2:3]
	v_pk_add_f32 v[4:5], v[48:49], v[50:51]
	v_mul_f32_e32 v62, v63, v63
	v_pk_add_f32 v[2:3], v[4:5], v[2:3]
	v_pk_add_f32 v[4:5], v[52:53], v[54:55]
	v_lshlrev_b32_e32 v105, 16, v189
	v_and_b32_e32 v41, 0xffff0000, v189
	v_pk_add_f32 v[2:3], v[4:5], v[2:3]
	v_pk_add_f32 v[4:5], v[56:57], v[58:59]
	v_mul_f32_e32 v104, v105, v105
	v_mul_f32_e32 v40, v41, v41
	v_lshlrev_b32_e32 v107, 16, v190
	v_and_b32_e32 v109, 0xffff0000, v190
	v_pk_add_f32 v[2:3], v[4:5], v[2:3]
	v_pk_add_f32 v[4:5], v[60:61], v[62:63]
	v_mul_f32_e32 v106, v107, v107
	v_mul_f32_e32 v108, v109, v109
	v_pk_add_f32 v[2:3], v[4:5], v[2:3]
	v_pk_add_f32 v[4:5], v[104:105], v[40:41]
	v_pk_add_f32 v[2:3], v[4:5], v[2:3]
	v_pk_add_f32 v[4:5], v[106:107], v[108:109]
	v_and_b32_e32 v7, 0xffff0000, v191
	v_pk_add_f32 v[4:5], v[4:5], v[2:3]
	v_lshlrev_b32_e32 v3, 16, v191
	v_mul_f32_e32 v2, v3, v3
	v_mul_f32_e32 v6, v7, v7
	v_pk_add_f32 v[6:7], v[2:3], v[6:7]
	v_pk_add_f32 v[4:5], v[6:7], v[4:5]
	s_waitcnt vmcnt(0) lgkmcnt(0)
	v_lshlrev_b32_e32 v43, 16, v192
	v_and_b32_e32 v45, 0xffff0000, v192
	v_mul_f32_e32 v42, v43, v43
	v_mul_f32_e32 v44, v45, v45
	v_lshlrev_b32_e32 v39, 16, v193
	v_and_b32_e32 v41, 0xffff0000, v193
	v_mul_f32_e32 v38, v39, v39
	v_mul_f32_e32 v40, v41, v41
	v_lshlrev_b32_e32 v35, 16, v194
	v_and_b32_e32 v37, 0xffff0000, v194
	v_pk_add_f32 v[6:7], v[42:43], v[44:45]
	v_mul_f32_e32 v34, v35, v35
	v_mul_f32_e32 v36, v37, v37
	v_lshlrev_b32_e32 v9, 16, v195
	v_and_b32_e32 v11, 0xffff0000, v195
	v_pk_add_f32 v[4:5], v[6:7], v[4:5]
	v_pk_add_f32 v[6:7], v[38:39], v[40:41]
	v_mul_f32_e32 v8, v9, v9
	v_mul_f32_e32 v10, v11, v11
	v_lshlrev_b32_e32 v47, 16, v196
	v_and_b32_e32 v49, 0xffff0000, v196
	v_pk_add_f32 v[4:5], v[6:7], v[4:5]
	v_pk_add_f32 v[6:7], v[34:35], v[36:37]
	v_mul_f32_e32 v46, v47, v47
	v_mul_f32_e32 v48, v49, v49
	v_lshlrev_b32_e32 v51, 16, v197
	v_and_b32_e32 v1, 0xffff0000, v197
	v_pk_add_f32 v[4:5], v[6:7], v[4:5]
	v_pk_add_f32 v[6:7], v[8:9], v[10:11]
	v_mul_f32_e32 v50, v51, v51
	v_mul_f32_e32 v0, v1, v1
	v_lshlrev_b32_e32 v53, 16, v198
	v_and_b32_e32 v55, 0xffff0000, v198
	v_pk_add_f32 v[4:5], v[6:7], v[4:5]
	v_pk_add_f32 v[6:7], v[46:47], v[48:49]
	v_mul_f32_e32 v52, v53, v53
	v_mul_f32_e32 v54, v55, v55
	v_lshlrev_b32_e32 v57, 16, v199
	v_and_b32_e32 v3, 0xffff0000, v199
	v_pk_add_f32 v[4:5], v[6:7], v[4:5]
	v_pk_add_f32 v[0:1], v[50:51], v[0:1]
	v_mul_f32_e32 v56, v57, v57
	v_mul_f32_e32 v2, v3, v3
	v_pk_add_f32 v[0:1], v[0:1], v[4:5]
	v_pk_add_f32 v[4:5], v[52:53], v[54:55]
	v_pk_add_f32 v[2:3], v[56:57], v[2:3]
	v_pk_add_f32 v[0:1], v[4:5], v[0:1]
	s_nop 0
	v_pk_add_f32 v[0:1], v[2:3], v[0:1]
	ds_bpermute_b32 v3, v216, v1
	ds_bpermute_b32 v2, v216, v0
	s_waitcnt lgkmcnt(0)
	v_pk_add_f32 v[0:1], v[0:1], v[2:3]
	ds_bpermute_b32 v3, v215, v1
	ds_bpermute_b32 v2, v215, v0
	s_and_saveexec_b64 s[0:1], s[8:9]
	s_cbranch_execz .LBB0_780
	s_waitcnt lgkmcnt(0)
	v_pk_add_f32 v[0:1], v[0:1], v[2:3]
	s_mov_b32 s16, 0x3b000000
	v_pk_mul_f32 v[0:1], v[0:1], s[16:17] op_sel_hi:[1,0]
	s_nop 0
	v_fma_f32 v0, -v1, v1, v0
	v_max_f32_e32 v0, 0, v0
	v_add_f32_e32 v0, 0x358637bd, v0
	v_mul_f32_e32 v2, 0x4b800000, v0
	v_cmp_gt_f32_e32 vcc, s33, v0
	s_nop 1
	v_cndmask_b32_e32 v0, v0, v2, vcc
	v_rsq_f32_e32 v0, v0
	s_nop 0
	v_mul_f32_e32 v2, 0x45800000, v0
	v_cndmask_b32_e32 v0, v0, v2, vcc
	ds_write2st64_b32 v64, v1, v0 offset0:136 offset1:138

; DI void phase_pooled(const Params& P) {
;     ...
;   for (int it = gtid; it < (T_TOK / 16) * 64; it += gn) {
;     const int seg = it >> 6, c8 = it & 63, g = c8 >> 4, win = 2 << g, t0 = seg * 16, s0 = t0 & 8191;
;     const u16* base = projB + (size_t)t0 * 512 + c8 * 8;
;     float run[8];
; #pragma unroll
;     for (int e = 0; e < 8; ++e) run[e] = 0.f;
.LBB0_787:
	s_setprio 0
	v_ashrrev_i32_e32 v10, 2, v26
	v_and_b32_e32 v6, -16, v10
	v_ashrrev_i32_e32 v7, 31, v6
	v_lshlrev_b64 v[8:9], 10, v[6:7]
	v_mov_b32_e32 v14, 0
	v_and_b32_e32 v29, 0x1ff0, v10
	v_lshl_add_u64 v[6:7], v[2:3], 0, v[8:9]
	s_mov_b32 s12, 1
	s_mov_b64 s[8:9], 0
	v_mov_b32_e32 v15, v14
	v_mov_b32_e32 v16, v14
	v_mov_b32_e32 v17, v14
	v_mov_b32_e32 v18, v14
	v_mov_b32_e32 v19, v14
	v_mov_b32_e32 v20, v14
	v_mov_b32_e32 v21, v14
	s_branch .LBB0_789

; template <int MF, int NF, bool SWAP = true>
; DI void gemm_main(f32x4 (&acc)[MF][NF], const u16* __restrict__ Ab, int lda, const u16* __restrict__ Bb, int ldb,
;                   int K, char* shm) {
;     ...
;   int sR0, sC0;
;   stage_rc<2>(wid * 1024 + lane * 16, sR0, sC0);
; #pragma unroll
;   for (int m = 0; m < MF; ++m)
; #pragma unroll
;     for (int n = 0; n < NF; ++n) acc[m][n] = f32x4{0.f, 0.f, 0.f, 0.f};
;   const int nt = K >> 6;
;   const int pa0 = sR0 * lda + sC0, pb0 = sR0 * ldb + sC0;
;     ...
;   const int a_off = lds_byte<2>(fr, fq * 8) + wr * (MF * 2048);
;   const int b_off = lds_byte<2>(fr, fq * 8) + wc * (NF * 2048);
;   G_STAGE(0, 0);
;   if constexpr (RING3) {
;     if (nt > 1) { G_STAGE(1, 1); asm volatile("s_waitcnt vmcnt(6)" ::: "memory"); }
;     else asm volatile("s_waitcnt vmcnt(0)" ::: "memory");
;     asm volatile("s_waitcnt lgkmcnt(0)" ::: "memory");
;     __builtin_amdgcn_s_barrier();
;   } else {
;     asm volatile("s_waitcnt vmcnt(0)" ::: "memory");
;     __syncthreads();
;   }
.LBB0_817:
	s_ashr_i32 s0, s16, 31
	s_lshr_b32 s0, s0, 29
	s_add_i32 s0, s16, s0
	s_ashr_i32 s1, s0, 3
	s_and_b32 s0, s0, -8
	s_sub_i32 s0, s16, s0
	s_lshr_b32 s4, s0, 31
	s_or_b32 s4, s4, 32
	s_mul_i32 s0, s4, s0
	s_add_i32 s0, s0, s1
	s_ashr_i32 s1, s0, 31
	s_lshr_b32 s1, s1, 28
	s_add_i32 s1, s0, s1
	s_ashr_i32 s4, s1, 4
	s_lshl_b32 s4, s4, 3
	s_sub_i32 s5, 0x80, s4
	s_min_u32 s5, s5, 8
	s_and_b32 s1, s1, -16
	s_sub_i32 s6, s0, s1
	v_cvt_f32_ubyte0_e32 v1, s5
	v_cvt_f32_i32_e32 v0, s6
	v_rcp_iflag_f32_e32 v2, v1
	s_ashr_i32 s0, s6, 30
	s_or_b32 s7, s0, 1
	v_mov_b32_e32 v10, v135
	v_mul_f32_e32 v2, v0, v2
	v_trunc_f32_e32 v2, v2
	v_fma_f32 v0, -v2, v1, v0
	v_cvt_i32_f32_e32 v2, v2
	v_cmp_ge_f32_e64 s[0:1], |v0|, v1
	s_and_b64 s[0:1], s[0:1], exec
	s_cselect_b32 s0, s7, 0
	v_readfirstlane_b32 s1, v2
	s_add_i32 s0, s1, s0
	s_sext_i32_i8 s1, s0
	s_mul_i32 s0, s0, s5
	s_sub_i32 s0, s6, s0
	s_sext_i32_i8 s0, s0
	s_add_i32 s4, s4, s0
	s_lshl_b32 s0, s4, 8
	s_lshl_b32 s8, s1, 8
	s_ashr_i32 s1, s0, 31
	s_lshl_b64 s[4:5], s[0:1], 10
	s_add_u32 s1, s10, s4
	v_lshlrev_b32_e32 v0, 4, v10
	v_and_b32_e32 v2, 32, v10
	v_ashrrev_i32_e32 v11, 6, v10
	v_lshrrev_b32_e32 v3, 31, v10
	v_bitop3_b32 v0, v0, v2, 48 bitop3:0x6c
	s_addc_u32 s7, s11, s5
	s_ashr_i32 s9, s8, 31
	v_add_u32_e32 v3, v11, v3
	v_lshrrev_b32_e32 v13, 1, v0
	v_lshlrev_b32_e32 v0, 7, v10
	s_lshl_b64 s[4:5], s[8:9], 1
	v_and_b32_e32 v1, 15, v10
	v_ashrrev_i32_e32 v12, 1, v3
	v_and_b32_e32 v3, 0x7fffffe, v3
	v_and_b32_e32 v14, 0x1e00, v0
	s_add_u32 s6, s1, s4
	v_sub_u32_e32 v3, v11, v3
	v_lshl_or_b32 v0, v12, 13, v14
	v_lshlrev_b32_e32 v15, 6, v1
	v_lshlrev_b32_e32 v1, 2, v10
	s_addc_u32 s7, s7, s5
	s_lshl_b64 s[8:9], s[8:9], 10
	v_lshl_add_u32 v0, v3, 5, v0
	v_and_b32_e32 v16, 32, v1
	v_lshlrev_b32_e32 v1, 6, v10
	s_add_u32 s1, s12, s8
	v_or_b32_e32 v0, v0, v13
	v_and_b32_e32 v130, 0xffffc000, v1
	v_lshlrev_b32_e32 v1, 13, v11
	s_addc_u32 s9, s13, s9
	v_lshlrev_b32_e32 v129, 10, v11
	v_and_b32_e32 v131, 0x6000, v1
	v_ashrrev_i32_e32 v1, 31, v0
	s_add_u32 s8, s1, s4
	v_lshlrev_b64 v[2:3], 1, v[0:1]
	v_readfirstlane_b32 s1, v129
	v_lshl_add_u64 v[4:5], s[6:7], 0, v[2:3]
	s_mov_b32 m0, s1
	s_mov_b64 s[18:19], 0x10000
	v_add_u32_e32 v1, 0x2000, v129
	v_add_u32_e32 v0, 0x10000, v0
	global_load_lds_dwordx4 v[4:5], off
	v_lshl_add_u64 v[4:5], v[2:3], 0, s[18:19]
	v_readfirstlane_b32 s1, v1
	v_ashrrev_i32_e32 v1, 31, v0
	v_add_u32_e32 v8, 0x4000, v129
	v_lshl_add_u64 v[6:7], s[6:7], 0, v[4:5]
	s_mov_b32 m0, s1
	v_lshlrev_b64 v[0:1], 1, v[0:1]
	v_readfirstlane_b32 s1, v8
	global_load_lds_dwordx4 v[6:7], off
	v_lshl_add_u64 v[6:7], s[6:7], 0, v[0:1]
	s_mov_b32 m0, s1
	s_mov_b64 s[18:19], 0x30000
	v_add_u32_e32 v17, 0x6000, v129
	global_load_lds_dwordx4 v[6:7], off
	v_lshl_add_u64 v[6:7], v[2:3], 0, s[18:19]
	v_readfirstlane_b32 s1, v17
	v_lshl_add_u64 v[8:9], s[6:7], 0, v[6:7]
	s_mov_b32 m0, s1
	s_addc_u32 s9, s9, s5
	global_load_lds_dwordx4 v[8:9], off
	v_and_b32_e32 v8, 48, v10
	v_bitop3_b32 v132, v15, v16, v8 bitop3:0x36
	v_add_u32_e32 v8, 0x8000, v129
	v_lshl_add_u64 v[2:3], s[8:9], 0, v[2:3]
	v_readfirstlane_b32 s1, v8
	s_mov_b32 m0, s1
	v_lshl_add_u64 v[0:1], s[8:9], 0, v[0:1]
	global_load_lds_dwordx4 v[2:3], off
	v_lshl_add_u64 v[2:3], s[8:9], 0, v[4:5]
	v_add_u32_e32 v4, 0xa000, v129
	s_mov_b32 s17, 0
	v_readfirstlane_b32 s1, v4
	s_mov_b32 m0, s1
	s_mov_b32 s18, 0
	global_load_lds_dwordx4 v[2:3], off
	v_add_u32_e32 v2, 0xc000, v129
	s_nop 0
	v_readfirstlane_b32 s1, v2
	v_add_u32_e32 v2, 0xe000, v129
	s_mov_b32 m0, s1
	v_readfirstlane_b32 s1, v2
	global_load_lds_dwordx4 v[0:1], off
	v_lshl_add_u64 v[0:1], s[8:9], 0, v[6:7]
	s_mov_b32 m0, s1
	s_movk_i32 s1, 0x1fc0
	global_load_lds_dwordx4 v[0:1], off
	s_waitcnt vmcnt(0)
	v_mul_lo_u32 v0, v12, s1
	v_or_b32_e32 v0, v13, v0
	v_lshlrev_b32_e32 v1, 5, v11
	v_mov_b32_e32 v12, 0
	v_add3_u32 v136, v0, v14, v1
	s_mov_b32 s1, 0
	v_mov_b32_e32 v13, v12
	v_mov_b32_e32 v14, v12
	v_mov_b32_e32 v15, v12
	v_mov_b32_e32 v0, v12
	v_mov_b32_e32 v1, v12
	v_mov_b32_e32 v2, v12
	v_mov_b32_e32 v3, v12
	v_mov_b32_e32 v4, v12
	v_mov_b32_e32 v5, v12
	v_mov_b32_e32 v6, v12
	v_mov_b32_e32 v7, v12
	v_mov_b32_e32 v8, v12
	v_mov_b32_e32 v9, v12
	v_mov_b32_e32 v10, v12
	v_mov_b32_e32 v11, v12
	v_mov_b32_e32 v16, v12
	v_mov_b32_e32 v17, v12
	v_mov_b32_e32 v18, v12
	v_mov_b32_e32 v19, v12
	v_mov_b32_e32 v20, v12
	v_mov_b32_e32 v21, v12
	v_mov_b32_e32 v22, v12
	v_mov_b32_e32 v23, v12
	v_mov_b32_e32 v24, v12
	v_mov_b32_e32 v25, v12
	v_mov_b32_e32 v26, v12
	v_mov_b32_e32 v27, v12
	v_mov_b32_e32 v28, v12
	v_mov_b32_e32 v29, v12
	v_mov_b32_e32 v30, v12
	v_mov_b32_e32 v31, v12
	v_mov_b32_e32 v32, v12
	v_mov_b32_e32 v33, v12
	v_mov_b32_e32 v34, v12
	v_mov_b32_e32 v35, v12
	v_mov_b32_e32 v36, v12
	v_mov_b32_e32 v37, v12
	v_mov_b32_e32 v38, v12
	v_mov_b32_e32 v39, v12
	v_mov_b32_e32 v40, v12
	v_mov_b32_e32 v41, v12
	v_mov_b32_e32 v42, v12
	v_mov_b32_e32 v43, v12
	v_mov_b32_e32 v44, v12
	v_mov_b32_e32 v45, v12
	v_mov_b32_e32 v46, v12
	v_mov_b32_e32 v47, v12
	v_mov_b32_e32 v48, v12
	v_mov_b32_e32 v49, v12
	v_mov_b32_e32 v50, v12
	v_mov_b32_e32 v51, v12
	v_mov_b32_e32 v52, v12
	v_mov_b32_e32 v53, v12
	v_mov_b32_e32 v54, v12
	v_mov_b32_e32 v55, v12
	v_mov_b32_e32 v56, v12
	v_mov_b32_e32 v57, v12
	v_mov_b32_e32 v58, v12
	v_mov_b32_e32 v59, v12
	v_mov_b32_e32 v60, v12
	v_mov_b32_e32 v61, v12
	v_mov_b32_e32 v62, v12
	v_mov_b32_e32 v63, v12
	v_mov_b32_e32 v64, v12
	v_mov_b32_e32 v65, v12
	v_mov_b32_e32 v66, v12
	v_mov_b32_e32 v67, v12
	v_mov_b32_e32 v68, v12
	v_mov_b32_e32 v69, v12
	v_mov_b32_e32 v70, v12
	v_mov_b32_e32 v71, v12
	v_mov_b32_e32 v72, v12
	v_mov_b32_e32 v73, v12
	v_mov_b32_e32 v74, v12
	v_mov_b32_e32 v75, v12
	v_mov_b32_e32 v76, v12
	v_mov_b32_e32 v77, v12
	v_mov_b32_e32 v78, v12
	v_mov_b32_e32 v79, v12
	v_mov_b32_e32 v80, v12
	v_mov_b32_e32 v81, v12
	v_mov_b32_e32 v82, v12
	v_mov_b32_e32 v83, v12
	v_mov_b32_e32 v84, v12
	v_mov_b32_e32 v85, v12
	v_mov_b32_e32 v86, v12
	v_mov_b32_e32 v87, v12
	v_mov_b32_e32 v88, v12
	v_mov_b32_e32 v89, v12
	v_mov_b32_e32 v90, v12
	v_mov_b32_e32 v91, v12
	v_mov_b32_e32 v92, v12
	v_mov_b32_e32 v93, v12
	v_mov_b32_e32 v94, v12
	v_mov_b32_e32 v95, v12
	v_mov_b32_e32 v96, v12
	v_mov_b32_e32 v97, v12
	v_mov_b32_e32 v98, v12
	v_mov_b32_e32 v99, v12
	v_mov_b32_e32 v100, v12
	v_mov_b32_e32 v101, v12
	v_mov_b32_e32 v102, v12
	v_mov_b32_e32 v103, v12
	v_mov_b32_e32 v104, v12
	v_mov_b32_e32 v105, v12
	v_mov_b32_e32 v106, v12
	v_mov_b32_e32 v107, v12
	v_mov_b32_e32 v108, v12
	v_mov_b32_e32 v109, v12
	v_mov_b32_e32 v110, v12
	v_mov_b32_e32 v111, v12
	v_mov_b32_e32 v112, v12
	v_mov_b32_e32 v113, v12
	v_mov_b32_e32 v114, v12
	v_mov_b32_e32 v115, v12
	v_mov_b32_e32 v116, v12
	v_mov_b32_e32 v117, v12
	v_mov_b32_e32 v118, v12
	v_mov_b32_e32 v119, v12
	v_mov_b32_e32 v120, v12
	v_mov_b32_e32 v121, v12
	v_mov_b32_e32 v122, v12
	v_mov_b32_e32 v123, v12
	v_mov_b32_e32 v124, v12
	v_mov_b32_e32 v125, v12
	v_mov_b32_e32 v126, v12
	v_mov_b32_e32 v127, v12
	s_waitcnt vmcnt(0) lgkmcnt(0)
	s_barrier
	s_nop 0
	s_nop 0
	s_branch .LBB0_819
